# attention tail: dummy L2 prefetch of this slot's z rows and the next slot's Q rows
# baseline (speedup 1.0000x reference)
; #define SBAR() __builtin_amdgcn_sched_barrier(0)
; __device__ __forceinline__ void attn_body(const bf16_t* __restrict__ Qb, const bf16_t* __restrict__ Kh, const bf16_t* __restrict__ Vh, const bf16_t* __restrict__ Zb, ...
;     ...
;     SBAR(); qkt(pB0, pB1, (bf16_t*)((char*)K_lds + SHM_K), qr, r32, hi);
;     finishSM(pA0, pA1, 1.f, l_reg, pa0, pa1, pa2, pa3); SBAR();
;     pv_d0(o, vb0, pa0, pa1, pa2, pa3); partialSM(pB0, pB1, negBC);
;     __syncthreads();
;     ...
;     u32x4 zr[8];
; #pragma unroll
;     for (int i = 0; i < 8; ++i) { const int idx = tid + 512 * i; zr[i] = *(const u32x4*)(Zb + (long)(idx >> 4) * LDP + (idx & 15) * 8); }
.Lat2_noshift_TA:
	s_waitcnt lgkmcnt(6)
	v_mfma_f32_32x32x16_bf16 v[0:15], v[160:163], v[236:239], v[0:15]
	ds_read_b64_tr_b16 v[236:237], v206 offset:512
	ds_read_b64_tr_b16 v[238:239], v206 offset:2560
	s_waitcnt lgkmcnt(6)
	v_mfma_f32_32x32x16_bf16 v[0:15], v[164:167], v[240:243], v[0:15]
	ds_read_b64_tr_b16 v[240:241], v206 offset:4608
	ds_read_b64_tr_b16 v[242:243], v206 offset:6656
	s_waitcnt vmcnt(0)
	ds_write_b128 v207, v[144:147] offset:16384
	v_exp_f32_e32 v181, v96
	v_exp_f32_e32 v221, v97
	s_waitcnt lgkmcnt(7)
	v_mfma_f32_32x32x16_bf16 v[0:15], v[168:171], v[244:247], v[0:15]
	ds_read_b64_tr_b16 v[244:245], v206 offset:8704
	ds_read_b64_tr_b16 v[246:247], v206 offset:10752
	ds_write_b128 v208, v[156:159] offset:16384
	v_exp_f32_e32 v222, v98
	v_exp_f32_e32 v223, v99
	s_waitcnt lgkmcnt(8)
	v_mfma_f32_32x32x16_bf16 v[0:15], v[172:175], v[248:251], v[0:15]
	ds_read_b64_tr_b16 v[248:249], v206 offset:12800
	ds_read_b64_tr_b16 v[250:251], v206 offset:14848
	v_exp_f32_e32 v224, v100
	v_exp_f32_e32 v225, v101
	s_waitcnt lgkmcnt(8)
	v_mfma_f32_32x32x16_bf16 v[16:31], v[160:163], v[236:239], v[16:31]
	ds_read_b64_tr_b16 v[236:237], v206 offset:1024
	ds_read_b64_tr_b16 v[238:239], v206 offset:3072
	v_exp_f32_e32 v226, v102
	v_exp_f32_e32 v227, v103
	s_waitcnt lgkmcnt(8)
	v_mfma_f32_32x32x16_bf16 v[16:31], v[164:167], v[240:243], v[16:31]
	ds_read_b64_tr_b16 v[240:241], v206 offset:5120
	ds_read_b64_tr_b16 v[242:243], v206 offset:7168
	v_exp_f32_e32 v228, v104
	v_exp_f32_e32 v229, v105
	s_waitcnt lgkmcnt(7)
	v_mfma_f32_32x32x16_bf16 v[16:31], v[168:171], v[244:247], v[16:31]
	ds_read_b64_tr_b16 v[244:245], v206 offset:9216
	ds_read_b64_tr_b16 v[246:247], v206 offset:11264
	v_lshrrev_b32_e32 v252, 1, v200
	v_mul_u32_u24_e32 v252, 0x1800, v252
	v_and_b32_e32 v253, 1, v200
	v_lshl_add_u32 v252, v253, 7, v252
	v_mov_b32_e32 v253, 0
	v_lshl_add_u64 v[252:253], s[16:17], 0, v[252:253]
	global_load_dword v252, v[252:253], off offset:3072
	v_exp_f32_e32 v230, v106
	v_exp_f32_e32 v231, v107
	s_waitcnt lgkmcnt(6)
	v_mfma_f32_32x32x16_bf16 v[16:31], v[172:175], v[248:251], v[16:31]
	ds_read_b64_tr_b16 v[248:249], v206 offset:13312
	ds_read_b64_tr_b16 v[250:251], v206 offset:15360
	v_exp_f32_e32 v232, v108
	v_exp_f32_e32 v233, v109
	s_waitcnt lgkmcnt(6)
	v_mfma_f32_32x32x16_bf16 v[32:47], v[160:163], v[236:239], v[32:47]
	ds_read_b64_tr_b16 v[236:237], v206 offset:1536
	ds_read_b64_tr_b16 v[238:239], v206 offset:3584
	v_exp_f32_e32 v234, v110
	v_exp_f32_e32 v235, v111
	s_waitcnt lgkmcnt(6)
	v_mfma_f32_32x32x16_bf16 v[32:47], v[164:167], v[240:243], v[32:47]
	ds_read_b64_tr_b16 v[240:241], v206 offset:5632
	ds_read_b64_tr_b16 v[242:243], v206 offset:7680
	v_exp_f32_e32 v80, v80
	v_exp_f32_e32 v81, v81
	s_waitcnt lgkmcnt(6)
	v_mfma_f32_32x32x16_bf16 v[32:47], v[168:171], v[244:247], v[32:47]
	ds_read_b64_tr_b16 v[244:245], v206 offset:9728
	ds_read_b64_tr_b16 v[246:247], v206 offset:11776
	v_exp_f32_e32 v82, v82
	v_exp_f32_e32 v83, v83
	s_waitcnt lgkmcnt(6)
	v_mfma_f32_32x32x16_bf16 v[32:47], v[172:175], v[248:251], v[32:47]
	ds_read_b64_tr_b16 v[248:249], v206 offset:13824
	ds_read_b64_tr_b16 v[250:251], v206 offset:15872
	v_exp_f32_e32 v84, v84
	v_exp_f32_e32 v85, v85
	s_waitcnt lgkmcnt(6)
	v_mfma_f32_32x32x16_bf16 v[48:63], v[160:163], v[236:239], v[48:63]
	v_exp_f32_e32 v86, v86
	v_exp_f32_e32 v87, v87
	s_waitcnt lgkmcnt(4)
	v_mfma_f32_32x32x16_bf16 v[48:63], v[164:167], v[240:243], v[48:63]
	v_exp_f32_e32 v88, v88
	v_exp_f32_e32 v89, v89
	v_exp_f32_e32 v90, v90
	s_waitcnt lgkmcnt(2)
	v_mfma_f32_32x32x16_bf16 v[48:63], v[168:171], v[244:247], v[48:63]
	v_exp_f32_e32 v91, v91
	v_exp_f32_e32 v92, v92
	v_exp_f32_e32 v93, v93
	s_waitcnt lgkmcnt(0)
	v_mfma_f32_32x32x16_bf16 v[48:63], v[172:175], v[248:251], v[48:63]
	v_exp_f32_e32 v94, v94
	v_exp_f32_e32 v95, v95
	s_waitcnt lgkmcnt(0)
	s_barrier
; #define SBAR() __builtin_amdgcn_sched_barrier(0)
; __device__ __forceinline__ void attn_body(const bf16_t* __restrict__ Qb, const bf16_t* __restrict__ Kh, const bf16_t* __restrict__ Vh, const bf16_t* __restrict__ Zb, ...
;     ...
;     finishSM(pB0, pB1, 1.f, l_reg, pa0, pa1, pa2, pa3); SBAR();
;     pv_d0(o, vb0 + (int)SHM_V, pa0, pa1, pa2, pa3);
;     __builtin_amdgcn_s_setprio(0);
;     if (hi == 0) li_l[r32] = l_reg; asm volatile("s_waitcnt lgkmcnt(0)" ::: "memory");
; __device__ void phase_attn(const Params& p, unsigned char* smem) {
;     ...
;     for (int slot_ = 0; slot_ < (REP_PH == 5 ? 16 : 8); ++slot_) { const int slot = slot_ & 7;
;         int pair, u, T, rb, hq, qb;
;         if (slot < 4) { pair = x + 8 * (slot >> 1); u = wl + 32 * (slot & 1); T = 4096; rb = (pair >> 1) * 4096; hq = u >> 4; qb = u & 15; }
;         else { pair = x + 8 * (slot - 4); u = wl; T = 2048; rb = NPROMPT + (pair >> 1) * 2048; hq = u >> 3; qb = u & 7; }
;         const int kvh = pair & 1, hg = kvh * 4 + hq; const size_t q0 = (size_t)rb + qb * 256;
;         att::attn_body(P1 + q0 * LDP + hg * 128, P1 + (size_t)rb * LDP + 1024 + kvh * 128, P1 + (size_t)rb * LDP + 1280 + kvh * 128,
	ds_read_b64_tr_b16 v[236:237], v205 offset:0
	ds_read_b64_tr_b16 v[238:239], v205 offset:2048
	ds_read_b64_tr_b16 v[240:241], v205 offset:4096
	ds_read_b64_tr_b16 v[242:243], v205 offset:6144
	ds_read_b64_tr_b16 v[244:245], v205 offset:8192
	ds_read_b64_tr_b16 v[246:247], v205 offset:10240
	ds_read_b64_tr_b16 v[248:249], v205 offset:12288
	ds_read_b64_tr_b16 v[250:251], v205 offset:14336
	v_add_f32_e32 v219, v181, v221
	v_cvt_pk_bf16_f32 v160, v181, v221
	v_add_f32_e32 v219, v222, v219
	v_cvt_pk_bf16_f32 v161, v222, v223
	v_add_f32_e32 v219, v223, v219
	v_cvt_pk_bf16_f32 v162, v224, v225
	v_add_f32_e32 v219, v224, v219
	v_cvt_pk_bf16_f32 v163, v226, v227
	v_add_f32_e32 v219, v225, v219
	v_cvt_pk_bf16_f32 v164, v228, v229
	v_add_f32_e32 v219, v226, v219
	v_cvt_pk_bf16_f32 v165, v230, v231
	v_add_f32_e32 v219, v227, v219
	v_cvt_pk_bf16_f32 v166, v232, v233
	v_add_f32_e32 v219, v228, v219
	v_cvt_pk_bf16_f32 v167, v234, v235
	v_add_f32_e32 v219, v229, v219
	v_cvt_pk_bf16_f32 v168, v80, v81
	v_add_f32_e32 v219, v230, v219
	v_cvt_pk_bf16_f32 v169, v82, v83
	v_add_f32_e32 v219, v231, v219
	v_cvt_pk_bf16_f32 v170, v84, v85
	v_add_f32_e32 v219, v232, v219
	v_cvt_pk_bf16_f32 v171, v86, v87
	v_add_f32_e32 v219, v233, v219
	v_cvt_pk_bf16_f32 v172, v88, v89
	v_add_f32_e32 v219, v234, v219
	v_cvt_pk_bf16_f32 v173, v90, v91
	v_add_f32_e32 v219, v235, v219
	v_cvt_pk_bf16_f32 v174, v92, v93
	v_add_f32_e32 v219, v80, v219
	v_cvt_pk_bf16_f32 v175, v94, v95
	v_add_f32_e32 v219, v81, v219
	v_permlane32_swap_b32_e32 v160, v162
	v_add_f32_e32 v219, v82, v219
	v_permlane32_swap_b32_e32 v161, v163
	v_add_f32_e32 v219, v83, v219
	v_permlane32_swap_b32_e32 v164, v166
	v_add_f32_e32 v219, v84, v219
	v_permlane32_swap_b32_e32 v165, v167
	v_add_f32_e32 v219, v85, v219
	v_permlane32_swap_b32_e32 v168, v170
	v_add_f32_e32 v219, v86, v219
	v_permlane32_swap_b32_e32 v169, v171
	v_add_f32_e32 v219, v87, v219
	v_permlane32_swap_b32_e32 v172, v174
	v_add_f32_e32 v219, v88, v219
	v_permlane32_swap_b32_e32 v173, v175
	v_add_f32_e32 v219, v89, v219
	v_add_f32_e32 v219, v90, v219
	v_add_f32_e32 v219, v91, v219
	v_add_f32_e32 v219, v92, v219
	v_add_f32_e32 v219, v93, v219
	v_add_f32_e32 v219, v94, v219
	v_add_f32_e32 v219, v95, v219
	v_mov_b32_e32 v220, v219
	s_nop 1
	v_permlane32_swap_b32_e32 v219, v220
	v_add_f32_e32 v219, v219, v220
	v_add_f32_e32 v204, v204, v219
	s_waitcnt lgkmcnt(6)
	v_mfma_f32_32x32x16_bf16 v[0:15], v[160:163], v[236:239], v[0:15]
	ds_read_b64_tr_b16 v[236:237], v205 offset:512
	ds_read_b64_tr_b16 v[238:239], v205 offset:2560
	s_waitcnt lgkmcnt(6)
	v_mfma_f32_32x32x16_bf16 v[0:15], v[164:167], v[240:243], v[0:15]
	ds_read_b64_tr_b16 v[240:241], v205 offset:4608
	ds_read_b64_tr_b16 v[242:243], v205 offset:6656
	s_waitcnt lgkmcnt(6)
	v_mfma_f32_32x32x16_bf16 v[0:15], v[168:171], v[244:247], v[0:15]
	ds_read_b64_tr_b16 v[244:245], v205 offset:8704
	ds_read_b64_tr_b16 v[246:247], v205 offset:10752
	s_cmp_lt_u32 s38, 7
	s_cbranch_scc0 .Lat2_noqpf
	s_add_i32 s14, s38, 1
	s_cmp_lt_u32 s14, 4
	s_cbranch_scc0 .Lat2_qpf_s
	s_lshr_b32 s15, s14, 1
	s_lshl_b32 s15, s15, 3
	s_add_i32 s15, s15, s3
	s_and_b32 s35, s14, 1
	s_lshl_b32 s35, s35, 5
	s_add_i32 s35, s35, s24
	s_lshr_b32 s40, s15, 1
	s_lshl_b32 s40, s40, 12
	s_lshr_b32 s41, s35, 4
	s_and_b32 s35, s35, 15
	s_branch .Lat2_qpf_j
.Lat2_qpf_s:
	s_add_i32 s15, s14, -4
	s_lshl_b32 s15, s15, 3
	s_add_i32 s15, s15, s3
	s_lshr_b32 s40, s15, 1
	s_lshl_b32 s40, s40, 11
	s_add_i32 s40, s40, 0x8000
	s_lshr_b32 s41, s24, 3
	s_and_b32 s35, s24, 7
.Lat2_qpf_j:
	s_and_b32 s15, s15, 1
	s_lshl_b32 s15, s15, 2
	s_add_i32 s41, s41, s15
	s_lshl_b32 s35, s35, 8
	s_add_i32 s40, s40, s35
	s_mul_hi_u32 s15, s40, 0x1800
	s_mul_i32 s40, s40, 0x1800
	s_lshl_b32 s41, s41, 8
	s_add_u32 s40, s40, s41
	s_addc_u32 s15, s15, 0
	s_add_u32 s40, s40, s78
	s_addc_u32 s41, s15, s79
	v_lshrrev_b32_e32 v222, 1, v200
	v_mul_u32_u24_e32 v222, 0x1800, v222
	v_and_b32_e32 v223, 1, v200
	v_lshl_add_u32 v222, v223, 7, v222
	v_mov_b32_e32 v223, 0
	v_lshl_add_u64 v[222:223], s[40:41], 0, v[222:223]
	global_load_dword v222, v[222:223], off
.Lat2_noqpf:
	s_waitcnt lgkmcnt(6)
	v_mfma_f32_32x32x16_bf16 v[0:15], v[172:175], v[248:251], v[0:15]
	ds_read_b64_tr_b16 v[248:249], v205 offset:12800
	ds_read_b64_tr_b16 v[250:251], v205 offset:14848
	s_waitcnt lgkmcnt(6)
	v_mfma_f32_32x32x16_bf16 v[16:31], v[160:163], v[236:239], v[16:31]
	ds_read_b64_tr_b16 v[236:237], v205 offset:1024
	ds_read_b64_tr_b16 v[238:239], v205 offset:3072
	s_waitcnt lgkmcnt(6)
	v_mfma_f32_32x32x16_bf16 v[16:31], v[164:167], v[240:243], v[16:31]
	ds_read_b64_tr_b16 v[240:241], v205 offset:5120
	ds_read_b64_tr_b16 v[242:243], v205 offset:7168
	s_waitcnt lgkmcnt(6)
	v_mfma_f32_32x32x16_bf16 v[16:31], v[168:171], v[244:247], v[16:31]
	ds_read_b64_tr_b16 v[244:245], v205 offset:9216
	ds_read_b64_tr_b16 v[246:247], v205 offset:11264
	s_waitcnt lgkmcnt(6)
	v_mfma_f32_32x32x16_bf16 v[16:31], v[172:175], v[248:251], v[16:31]
	ds_read_b64_tr_b16 v[248:249], v205 offset:13312
	ds_read_b64_tr_b16 v[250:251], v205 offset:15360
	s_waitcnt lgkmcnt(6)
	v_mfma_f32_32x32x16_bf16 v[32:47], v[160:163], v[236:239], v[32:47]
	ds_read_b64_tr_b16 v[236:237], v205 offset:1536
	ds_read_b64_tr_b16 v[238:239], v205 offset:3584
	s_waitcnt lgkmcnt(6)
	v_mfma_f32_32x32x16_bf16 v[32:47], v[164:167], v[240:243], v[32:47]
	ds_read_b64_tr_b16 v[240:241], v205 offset:5632
	ds_read_b64_tr_b16 v[242:243], v205 offset:7680
	s_waitcnt lgkmcnt(6)
	v_mfma_f32_32x32x16_bf16 v[32:47], v[168:171], v[244:247], v[32:47]
	ds_read_b64_tr_b16 v[244:245], v205 offset:9728
	ds_read_b64_tr_b16 v[246:247], v205 offset:11776
	s_waitcnt lgkmcnt(6)
	v_mfma_f32_32x32x16_bf16 v[32:47], v[172:175], v[248:251], v[32:47]
	ds_read_b64_tr_b16 v[248:249], v205 offset:13824
	ds_read_b64_tr_b16 v[250:251], v205 offset:15872
	s_waitcnt lgkmcnt(6)
	v_mfma_f32_32x32x16_bf16 v[48:63], v[160:163], v[236:239], v[48:63]
	s_waitcnt lgkmcnt(4)
	v_mfma_f32_32x32x16_bf16 v[48:63], v[164:167], v[240:243], v[48:63]
	s_waitcnt lgkmcnt(2)
	v_mfma_f32_32x32x16_bf16 v[48:63], v[168:171], v[244:247], v[48:63]
	s_waitcnt lgkmcnt(0)
	v_mfma_f32_32x32x16_bf16 v[48:63], v[172:175], v[248:251], v[48:63]
.Lat2_after_tail:
	v_mov_b32_e32 v64, 0
	v_mov_b32_e32 v65, 0
	v_mov_b32_e32 v67, 0
	v_mov_b32_e32 v68, 0
	v_and_b32_e32 v66, 0x3fffffc0, v200
	v_lshl_add_u32 v66, v66, 2, s36
	s_setprio 0
	v_cmp_gt_u32_e32 vcc, 32, v203
	s_and_saveexec_b64 s[6:7], vcc
	s_cbranch_execz .LBB0_480
	v_add_f32_e32 v64, v64, v65
	v_add_f32_e32 v64, v204, v64
	v_add_f32_e32 v67, v67, v68
	v_lshl_add_u32 v65, v201, 2, v66
	v_add_f32_e32 v64, v64, v67
	ds_write_b32 v65, v64
	s_branch .LBB0_480
